# XCD-local grid barriers (8 GEMM-to-GEMM seams) with runtime blockIdx%8-XCC mapping check and global fallback
# speedup vs baseline: 1.0077x; 1.0077x over previous
.LBB0_57:
	s_or_b64 exec, exec, s[4:5]
	s_load_dwordx2 s[78:79], s[0:1], 0xe0
	s_mov_b32 s7, 0
	v_cmp_eq_u32_e64 s[24:25], 0, v176
	s_barrier
	s_waitcnt lgkmcnt(0)
	s_and_saveexec_b64 s[4:5], s[24:25]
	s_cbranch_execz .LBB0_59
	s_mov_b64 s[8:9], s[0:1]
	v_mov_b32_e32 v2, 1
	v_mov_b64_e32 v[0:1], s[8:9]
	flat_load_dwordx2 v[0:1], v[0:1] offset:216
	s_getreg_b32 s3, hwreg(HW_REG_XCC_ID, 0, 4)
	s_lshl_b32 s3, s3, 8
	s_and_b32 s6, s3, 0xf00
	s_waitcnt vmcnt(0) lgkmcnt(0)
	s_lshr_b32 s98, s3, 8
	s_and_b32 s98, s98, 15
	s_lshl_b32 s98, 1, s98
	s_and_b32 s99, s2, 7
	s_lshl_b32 s99, s99, 2
	s_add_u32 s100, s99, 64
	s_mov_b32 s101, 0
	v_lshl_add_u64 v[4:5], v[0:1], 0, s[100:101]
	v_mov_b32_e32 v3, s98
	global_atomic_or v[4:5], v3, off
	v_lshl_add_u64 v[0:1], v[0:1], 0, s[6:7]
	global_atomic_add v[0:1], v2, off offset:1024

.LBB0_124:
	s_or_b64 exec, exec, s[38:39]
	s_mov_b64 s[4:5], s[0:1]
	s_waitcnt lgkmcnt(0)
	s_barrier
	s_load_dwordx2 s[98:99], s[0:1], 0xd8
	v_mov_b32_e32 v10, 0
	v_mov_b32_e32 v11, 0
	s_waitcnt lgkmcnt(0)
	global_load_dwordx4 v[0:3], v10, s[98:99] offset:64 sc1
	global_load_dwordx4 v[4:7], v10, s[98:99] offset:80 sc1
	s_waitcnt vmcnt(0)
	v_or3_b32 v8, v0, v1, v2
	v_or3_b32 v8, v8, v3, v4
	v_or3_b32 v8, v8, v5, v6
	v_or_b32_e32 v8, v8, v7
	v_add_u32_e32 v9, -1, v0
	v_and_b32_e32 v9, v9, v0
	v_or_b32_e32 v11, v11, v9
	v_add_u32_e32 v9, -1, v1
	v_and_b32_e32 v9, v9, v1
	v_or_b32_e32 v11, v11, v9
	v_add_u32_e32 v9, -1, v2
	v_and_b32_e32 v9, v9, v2
	v_or_b32_e32 v11, v11, v9
	v_add_u32_e32 v9, -1, v3
	v_and_b32_e32 v9, v9, v3
	v_or_b32_e32 v11, v11, v9
	v_add_u32_e32 v9, -1, v4
	v_and_b32_e32 v9, v9, v4
	v_or_b32_e32 v11, v11, v9
	v_add_u32_e32 v9, -1, v5
	v_and_b32_e32 v9, v9, v5
	v_or_b32_e32 v11, v11, v9
	v_add_u32_e32 v9, -1, v6
	v_and_b32_e32 v9, v9, v6
	v_or_b32_e32 v11, v11, v9
	v_add_u32_e32 v9, -1, v7
	v_and_b32_e32 v9, v9, v7
	v_or_b32_e32 v11, v11, v9
	v_xor_b32_e32 v8, 0xff, v8
	v_or_b32_e32 v8, v8, v11
	s_nop 0
	v_readfirstlane_b32 s98, v8
	s_cmp_eq_u32 s98, 0
	s_cselect_b32 s98, 1, 0
	v_writelane_b32 v254, s98, 2
	s_cmpk_lt_i32 s2, 0x200
	v_mov_b64_e32 v[0:1], s[4:5]
	flat_load_dwordx2 v[0:1], v[0:1] offset:216
	v_mov_b32_e32 v10, v176
	s_cselect_b64 s[46:47], -1, 0
	s_and_b64 vcc, exec, s[46:47]
	v_readfirstlane_b32 s6, v10
	s_cbranch_vccz .LBB0_130
	s_lshr_b32 s3, s33, 29
	s_add_i32 s3, s2, s3
	s_and_b32 s4, s3, -8
	s_sub_i32 s7, s2, s4
	s_cmp_gt_i32 s7, -1
	s_cbranch_scc0 .LBB0_127
	s_lshl_b32 s8, s7, 6
	s_cbranch_execz .LBB0_128
	s_branch .LBB0_129

.LBB0_231:
	s_andn2_saveexec_b64 s[6:7], s[6:7]
	s_cbranch_execz .LBB0_247
	v_readlane_b32 s98, v254, 2
	s_nop 0
	s_cmp_lg_u32 s98, 0
	s_cbranch_scc1 .Llb_fast_1
	v_add_co_u32_e32 v6, vcc, 0x3000, v0
	buffer_wbl2 sc1
	s_waitcnt lgkmcnt(0)
	s_waitcnt vmcnt(0)
	v_addc_co_u32_e32 v7, vcc, 0, v1, vcc
	v_mov_b32_e32 v5, 1
	global_atomic_add v5, v[6:7], v5, off offset:1024 sc0
	v_cvt_f32_u32_e32 v6, v4
	v_sub_u32_e32 v8, 0, v4
	s_mov_b64 s[6:7], 0x3500
	s_mov_b64 s[8:9], -1
	v_rcp_iflag_f32_e32 v6, v6
	s_nop 0
	v_mul_f32_e32 v6, 0x4f7ffffe, v6
	v_cvt_u32_f32_e32 v9, v6
	v_lshl_add_u64 v[6:7], v[0:1], 0, s[6:7]
	v_mul_lo_u32 v8, v8, v9
	v_mul_hi_u32 v8, v9, v8
	v_add_u32_e32 v8, v9, v8
	s_waitcnt vmcnt(0)
	v_mul_hi_u32 v8, v5, v8
	v_mul_lo_u32 v10, v8, v4
	v_add_u32_e32 v9, 1, v5
	v_sub_u32_e32 v5, v5, v10
	v_add_u32_e32 v11, 1, v8
	v_cmp_ge_u32_e32 vcc, v5, v4
	v_sub_u32_e32 v10, v5, v4
	s_nop 0
	v_cndmask_b32_e32 v8, v8, v11, vcc
	v_cndmask_b32_e32 v5, v5, v10, vcc
	v_add_u32_e32 v10, 1, v8
	v_cmp_ge_u32_e32 vcc, v5, v4
	s_nop 1
	v_cndmask_b32_e32 v8, v8, v10, vcc
	v_mad_u64_u32 v[4:5], s[6:7], v4, v8, v[4:5]
	v_cmp_ne_u32_e32 vcc, v9, v4
	s_and_saveexec_b64 s[6:7], vcc
	s_cbranch_execz .LBB0_244
	global_load_dword v4, v[6:7], off sc1
	s_mov_b64 s[10:11], 0
	s_waitcnt vmcnt(0)
	v_cmp_eq_u32_e32 vcc, v4, v8
	s_and_saveexec_b64 s[8:9], vcc
	s_cbranch_execz .LBB0_243
	s_mov_b64 s[10:11], 0x200
	v_lshl_add_u64 v[4:5], v[0:1], 0, s[10:11]
	s_mov_b32 s3, 1
	s_mov_b64 s[10:11], 0
	s_branch .LBB0_236

.Llb_fast_1:
	v_add_co_u32_e32 v0, vcc, 0x2000, v2
	v_mov_b32_e32 v2, 1
	s_nop 0
	v_addc_co_u32_e32 v1, vcc, 0, v3, vcc
	s_waitcnt vmcnt(0)
	buffer_inv sc1
	global_atomic_add v[0:1], v2, off offset:1024
	s_waitcnt vmcnt(0)

.LBB0_657:
	s_andn2_saveexec_b64 s[8:9], s[8:9]
	s_cbranch_execz .LBB0_673
	v_readlane_b32 s98, v254, 2
	s_nop 0
	s_cmp_lg_u32 s98, 0
	s_cbranch_scc1 .Llb_fast_6
	v_add_co_u32_e32 v6, vcc, 0x3000, v0
	buffer_wbl2 sc1
	s_waitcnt lgkmcnt(0)
	s_waitcnt vmcnt(0)
	v_addc_co_u32_e32 v7, vcc, 0, v1, vcc
	v_mov_b32_e32 v5, 1
	global_atomic_add v5, v[6:7], v5, off offset:1024 sc0
	v_cvt_f32_u32_e32 v6, v4
	v_sub_u32_e32 v8, 0, v4
	s_mov_b64 s[8:9], 0x3500
	s_mov_b64 s[10:11], -1
	v_rcp_iflag_f32_e32 v6, v6
	s_nop 0
	v_mul_f32_e32 v6, 0x4f7ffffe, v6
	v_cvt_u32_f32_e32 v9, v6
	v_lshl_add_u64 v[6:7], v[0:1], 0, s[8:9]
	v_mul_lo_u32 v8, v8, v9
	v_mul_hi_u32 v8, v9, v8
	v_add_u32_e32 v8, v9, v8
	s_waitcnt vmcnt(0)
	v_mul_hi_u32 v8, v5, v8
	v_mul_lo_u32 v10, v8, v4
	v_add_u32_e32 v9, 1, v5
	v_sub_u32_e32 v5, v5, v10
	v_add_u32_e32 v11, 1, v8
	v_cmp_ge_u32_e32 vcc, v5, v4
	v_sub_u32_e32 v10, v5, v4
	s_nop 0
	v_cndmask_b32_e32 v8, v8, v11, vcc
	v_cndmask_b32_e32 v5, v5, v10, vcc
	v_add_u32_e32 v10, 1, v8
	v_cmp_ge_u32_e32 vcc, v5, v4
	s_nop 1
	v_cndmask_b32_e32 v8, v8, v10, vcc
	v_mad_u64_u32 v[4:5], s[8:9], v4, v8, v[4:5]
	v_cmp_ne_u32_e32 vcc, v9, v4
	s_and_saveexec_b64 s[8:9], vcc
	s_cbranch_execz .LBB0_670
	global_load_dword v4, v[6:7], off sc1
	s_mov_b64 s[12:13], 0
	s_waitcnt vmcnt(0)
	v_cmp_eq_u32_e32 vcc, v4, v8
	s_and_saveexec_b64 s[10:11], vcc
	s_cbranch_execz .LBB0_669
	s_mov_b64 s[12:13], 0x200
	v_lshl_add_u64 v[4:5], v[0:1], 0, s[12:13]
	s_mov_b32 s3, 1
	s_mov_b64 s[12:13], 0
	s_branch .LBB0_662

	.amdhsa_kernel _Z9hymba_fwd4Args
		.amdhsa_group_segment_fixed_size 0
		.amdhsa_private_segment_fixed_size 0
		.amdhsa_kernarg_size 480
		.amdhsa_user_sgpr_count 2
		.amdhsa_user_sgpr_dispatch_ptr 0
		.amdhsa_user_sgpr_queue_ptr 0
		.amdhsa_user_sgpr_kernarg_segment_ptr 1
		.amdhsa_user_sgpr_dispatch_id 0
		.amdhsa_user_sgpr_kernarg_preload_length 0
		.amdhsa_user_sgpr_kernarg_preload_offset 0
		.amdhsa_user_sgpr_private_segment_size 0
		.amdhsa_uses_dynamic_stack 0
		.amdhsa_enable_private_segment 0
		.amdhsa_system_sgpr_workgroup_id_x 1
		.amdhsa_system_sgpr_workgroup_id_y 0
		.amdhsa_system_sgpr_workgroup_id_z 0
		.amdhsa_system_sgpr_workgroup_info 0
		.amdhsa_system_vgpr_workitem_id 2
		.amdhsa_next_free_vgpr 255
		.amdhsa_next_free_sgpr 102
		.amdhsa_accum_offset 256
		.amdhsa_reserve_vcc 1
		.amdhsa_float_round_mode_32 0
		.amdhsa_float_round_mode_16_64 0
		.amdhsa_float_denorm_mode_32 3
		.amdhsa_float_denorm_mode_16_64 3
		.amdhsa_dx10_clamp 1
		.amdhsa_ieee_mode 1
		.amdhsa_fp16_overflow 0
		.amdhsa_tg_split 0
		.amdhsa_exception_fp_ieee_invalid_op 0
		.amdhsa_exception_fp_denorm_src 0
		.amdhsa_exception_fp_ieee_div_zero 0
		.amdhsa_exception_fp_ieee_overflow 0
		.amdhsa_exception_fp_ieee_underflow 0
		.amdhsa_exception_fp_ieee_inexact 0
		.amdhsa_exception_int_div_zero 0
	.end_amdhsa_kernel

amdhsa.kernels:
  - .agpr_count:     0
    .args:
      - .offset:         0
        .size:           224
        .value_kind:     by_value
      - .offset:         224
        .size:           4
        .value_kind:     hidden_block_count_x
      - .offset:         228
        .size:           4
        .value_kind:     hidden_block_count_y
      - .offset:         232
        .size:           4
        .value_kind:     hidden_block_count_z
      - .offset:         236
        .size:           2
        .value_kind:     hidden_group_size_x
      - .offset:         238
        .size:           2
        .value_kind:     hidden_group_size_y
      - .offset:         240
        .size:           2
        .value_kind:     hidden_group_size_z
      - .offset:         242
        .size:           2
        .value_kind:     hidden_remainder_x
      - .offset:         244
        .size:           2
        .value_kind:     hidden_remainder_y
      - .offset:         246
        .size:           2
        .value_kind:     hidden_remainder_z
      - .offset:         264
        .size:           8
        .value_kind:     hidden_global_offset_x
      - .offset:         272
        .size:           8
        .value_kind:     hidden_global_offset_y
      - .offset:         280
        .size:           8
        .value_kind:     hidden_global_offset_z
      - .offset:         288
        .size:           2
        .value_kind:     hidden_grid_dims
      - .offset:         312
        .size:           8
        .value_kind:     hidden_multigrid_sync_arg
      - .offset:         344
        .size:           4
        .value_kind:     hidden_dynamic_lds_size
    .group_segment_fixed_size: 0
    .kernarg_segment_align: 8
    .kernarg_segment_size: 480
    .language:       OpenCL C
    .language_version:
      - 2
      - 0
    .max_flat_workgroup_size: 512
    .name:           _Z9hymba_fwd4Args
    .private_segment_fixed_size: 0
    .sgpr_count:     108
    .sgpr_spill_count: 2
    .symbol:         _Z9hymba_fwd4Args.kd
    .uniform_work_group_size: 1
    .uses_dynamic_stack: false
    .vgpr_count:     255
    .vgpr_spill_count: 0
    .wavefront_size: 64
